# v46 plus removal of 42 provably redundant lgkmcnt waits in front of the QK MFMAs of the attention loop
# speedup vs baseline: 1.0061x; 1.0008x over previous
; #define WAIT_BAR(N) asm volatile("s_waitcnt vmcnt(" #N ") lgkmcnt(0)\n\ts_barrier":::"memory")
;   #define RESC() do{ if(resc){ asm volatile("s_waitcnt lgkmcnt(0)":::"memory"); \
;       _Pragma("unroll") for(int d_=0;d_<2;++d_) _Pragma("unroll") for(int r=0;r<16;++r)o[d_][r]*=wsf[crow(r,hi)]; } }while(0)
;   #define ROT() do{sl_prev=sl_cur;sl_cur=sl_next;sl_next=(sl_next==(NSLOT-1)*SLOTB)?0:sl_next+SLOTB;}while(0)
; template<int THRL> __device__ __forceinline__ void attn_unit(const bf16*Qu,const bf16*__restrict__ Kh,const bf16*__restrict__ Vh,bf16*Ou,const int NT,const float shift,char*shm){
;     ...
;   int t=1;
;     ...
;   for(;t+5<NT;t+=2){
;     STEP(pB0,pB1,pA0,pA1,t,true,true,true);     WAIT_BAR(2); RESC(); ROT();
;     STEP(pA0,pA1,pB0,pB1,t+1,true,true,true);   WAIT_BAR(2); RESC(); ROT();
.LBB0_618:
	s_mov_b32 s4, s76
	s_mov_b32 s5, s26
	s_mov_b32 s25, s31
	ds_read_b64_tr_b16 v[52:53], v199 offset:24576
	ds_read_b64_tr_b16 v[54:55], v199 offset:25088
	v_mfma_f32_32x32x16_bf16 v[114:129], v[190:193], v[150:153], v[34:49]
	v_add_f32_e32 v50, v82, v50
	v_add_f32_e32 v194, v83, v194
	v_add_f32_e32 v195, v84, v195
	v_add_f32_e32 v196, v85, v196
	v_add_f32_e32 v50, v86, v50
	v_add_f32_e32 v194, v87, v194
	v_cvt_pk_bf16_f32 v158, v82, v83
	v_cvt_pk_bf16_f32 v159, v84, v85
	ds_read_b64_tr_b16 v[60:61], v199 offset:28672
	ds_read_b64_tr_b16 v[62:63], v199 offset:29184
	v_mfma_f32_32x32x16_bf16 v[98:113], v[186:189], v[150:153], v[34:49]
	v_add_f32_e32 v195, v88, v195
	v_add_f32_e32 v196, v89, v196
	v_add_f32_e32 v50, v90, v50
	v_add_f32_e32 v194, v91, v194
	v_cvt_pk_bf16_f32 v160, v86, v87
	v_cvt_pk_bf16_f32 v161, v88, v89
	ds_read_b64_tr_b16 v[82:83], v199 offset:25600
	ds_read_b64_tr_b16 v[84:85], v199 offset:26112
	v_mfma_f32_32x32x16_bf16 v[114:129], v[182:185], v[138:141], v[114:129]
	v_add_f32_e32 v195, v92, v195
	v_add_f32_e32 v196, v93, v196
	v_add_f32_e32 v50, v94, v50
	v_add_f32_e32 v194, v95, v194
	v_cvt_pk_bf16_f32 v154, v90, v91
	v_cvt_pk_bf16_f32 v155, v92, v93
	ds_read_b64_tr_b16 v[86:87], v199 offset:29696
	ds_read_b64_tr_b16 v[88:89], v199 offset:30208
	v_mfma_f32_32x32x16_bf16 v[98:113], v[178:181], v[138:141], v[98:113]
	v_add_f32_e32 v195, v96, v195
	v_add_f32_e32 v196, v97, v196
	v_add_f32_e32 v50, v66, v50
	v_add_f32_e32 v194, v67, v194
	v_cvt_pk_bf16_f32 v156, v94, v95
	v_cvt_pk_bf16_f32 v157, v96, v97
	ds_read_b64_tr_b16 v[90:91], v199 offset:26624
	ds_read_b64_tr_b16 v[92:93], v199 offset:27136
	v_mfma_f32_32x32x16_bf16 v[114:129], v[174:177], v[134:137], v[114:129]
	v_add_f32_e32 v195, v68, v195
	v_add_f32_e32 v196, v69, v196
	v_add_f32_e32 v50, v70, v50
	v_add_f32_e32 v194, v71, v194
	v_cvt_pk_bf16_f32 v146, v66, v67
	v_cvt_pk_bf16_f32 v147, v68, v69
	ds_read_b64_tr_b16 v[64:65], v199 offset:30720
	ds_read_b64_tr_b16 v[66:67], v199 offset:31232
	v_mfma_f32_32x32x16_bf16 v[98:113], v[170:173], v[134:137], v[98:113]
	v_add_f32_e32 v195, v72, v195
	v_add_f32_e32 v196, v73, v196
	v_add_f32_e32 v50, v74, v50
	v_add_f32_e32 v194, v75, v194
	v_cvt_pk_bf16_f32 v148, v70, v71
	v_cvt_pk_bf16_f32 v149, v72, v73
	ds_read_b64_tr_b16 v[68:69], v199 offset:27648
	ds_read_b64_tr_b16 v[70:71], v199 offset:28160
	v_mfma_f32_32x32x16_bf16 v[114:129], v[166:169], v[130:133], v[114:129]
	v_add_f32_e32 v195, v76, v195
	v_add_f32_e32 v196, v77, v196
	v_add_f32_e32 v50, v78, v50
	v_add_f32_e32 v194, v79, v194
	v_cvt_pk_bf16_f32 v142, v74, v75
	v_cvt_pk_bf16_f32 v143, v76, v77
	ds_read_b64_tr_b16 v[72:73], v199 offset:31744
	ds_read_b64_tr_b16 v[74:75], v199 offset:32256
	v_mfma_f32_32x32x16_bf16 v[98:113], v[162:165], v[130:133], v[98:113]
	v_add_f32_e32 v195, v80, v195
	v_add_f32_e32 v196, v81, v196
	v_cvt_pk_bf16_f32 v144, v78, v79
	v_cvt_pk_bf16_f32 v145, v80, v81
	s_add_i32 s6, s31, s70
	s_mov_b32 s7, m0
	s_mov_b32 m0, s6
	s_nop 0
	global_load_lds_dwordx4 v197, s[98:99]
	s_mov_b32 m0, s7
	s_add_i32 s6, s76, s71
	s_mov_b32 s7, m0
	s_mov_b32 m0, s6
	s_nop 0
	global_load_lds_dwordx4 v197, s[100:101]
	s_mov_b32 m0, s7
	s_add_u32 s98, s98, 0x2000
	s_addc_u32 s99, s99, 0
	s_add_u32 s100, s100, 0x2000
	s_addc_u32 s101, s101, 0
	s_waitcnt lgkmcnt(14)
	v_mfma_f32_32x32x16_bf16 v[2:17], v[158:161], v[52:55], v[2:17]
	v_exp_f32_e32 v114, v114
	v_exp_f32_e32 v115, v115
	v_exp_f32_e32 v116, v116
	v_exp_f32_e32 v117, v117
	s_waitcnt lgkmcnt(12)
	v_mfma_f32_32x32x16_bf16 v[18:33], v[158:161], v[60:63], v[18:33]
	v_exp_f32_e32 v118, v118
	v_exp_f32_e32 v119, v119
	v_exp_f32_e32 v120, v120
	v_exp_f32_e32 v121, v121
	ds_read_b128 v[60:63], v204
	ds_read_b128 v[162:165], v204 offset:512
	s_waitcnt lgkmcnt(12)
	v_mfma_f32_32x32x16_bf16 v[2:17], v[154:157], v[82:85], v[2:17]
	v_exp_f32_e32 v122, v122
	v_exp_f32_e32 v123, v123
	v_exp_f32_e32 v124, v124
	v_exp_f32_e32 v125, v125
	ds_read_b128 v[166:169], v204 offset:2048
	ds_read_b128 v[170:173], v204 offset:2560
	s_waitcnt lgkmcnt(12)
	v_mfma_f32_32x32x16_bf16 v[18:33], v[154:157], v[86:89], v[18:33]
	v_exp_f32_e32 v126, v126
	v_exp_f32_e32 v127, v127
	v_exp_f32_e32 v128, v128
	v_exp_f32_e32 v129, v129
	ds_read_b128 v[174:177], v204 offset:4096
	ds_read_b128 v[178:181], v204 offset:4608
	s_waitcnt lgkmcnt(12)
	v_mfma_f32_32x32x16_bf16 v[2:17], v[146:149], v[90:93], v[2:17]
	v_exp_f32_e32 v98, v98
	v_exp_f32_e32 v99, v99
	v_exp_f32_e32 v100, v100
	v_exp_f32_e32 v101, v101
	ds_read_b128 v[182:185], v204 offset:6144
	ds_read_b128 v[52:55], v204 offset:6656
	s_waitcnt lgkmcnt(12)
	v_mfma_f32_32x32x16_bf16 v[18:33], v[146:149], v[64:67], v[18:33]
	v_exp_f32_e32 v102, v102
	v_exp_f32_e32 v103, v103
	v_exp_f32_e32 v104, v104
	v_exp_f32_e32 v105, v105
	s_waitcnt lgkmcnt(10)
	v_mfma_f32_32x32x16_bf16 v[2:17], v[142:145], v[68:71], v[2:17]
	v_exp_f32_e32 v106, v106
	v_exp_f32_e32 v107, v107
	v_exp_f32_e32 v108, v108
	v_exp_f32_e32 v109, v109
	s_waitcnt lgkmcnt(8)
	v_mfma_f32_32x32x16_bf16 v[18:33], v[142:145], v[72:75], v[18:33]
	v_exp_f32_e32 v110, v110
	v_exp_f32_e32 v111, v111
	v_exp_f32_e32 v112, v112
	v_exp_f32_e32 v113, v113
	s_waitcnt vmcnt(2) lgkmcnt(0)
	s_barrier
; #define WAIT_BAR(N) asm volatile("s_waitcnt vmcnt(" #N ") lgkmcnt(0)\n\ts_barrier":::"memory")
;   #define RESC() do{ if(resc){ asm volatile("s_waitcnt lgkmcnt(0)":::"memory"); \
;       _Pragma("unroll") for(int d_=0;d_<2;++d_) _Pragma("unroll") for(int r=0;r<16;++r)o[d_][r]*=wsf[crow(r,hi)]; } }while(0)
;   #define ROT() do{sl_prev=sl_cur;sl_cur=sl_next;sl_next=(sl_next==(NSLOT-1)*SLOTB)?0:sl_next+SLOTB;}while(0)
; template<int THRL> __device__ __forceinline__ void attn_unit(const bf16*Qu,const bf16*__restrict__ Kh,const bf16*__restrict__ Vh,bf16*Ou,const int NT,const float shift,char*shm){
;     ...
;   int t=1;
;     ...
;   for(;t+5<NT;t+=2){
;     STEP(pB0,pB1,pA0,pA1,t,true,true,true);     WAIT_BAR(2); RESC(); ROT();
;     STEP(pA0,pA1,pB0,pB1,t+1,true,true,true);   WAIT_BAR(2); RESC(); ROT();
;   }
	s_add_i32 s6, s76, 0x2000
	s_cmpk_lg_i32 s76, 0x4000
	s_cselect_b32 s31, s6, 0
	ds_read_b64_tr_b16 v[186:187], v200 offset:24576
	ds_read_b64_tr_b16 v[188:189], v200 offset:25088
	v_mfma_f32_32x32x16_bf16 v[82:97], v[60:63], v[150:153], v[34:49]
	v_add_f32_e32 v50, v114, v50
	v_add_f32_e32 v194, v115, v194
	v_add_f32_e32 v195, v116, v195
	v_add_f32_e32 v196, v117, v196
	v_add_f32_e32 v50, v118, v50
	v_add_f32_e32 v194, v119, v194
	v_cvt_pk_bf16_f32 v158, v114, v115
	v_cvt_pk_bf16_f32 v159, v116, v117
	ds_read_b64_tr_b16 v[60:61], v200 offset:28672
	ds_read_b64_tr_b16 v[62:63], v200 offset:29184
	v_mfma_f32_32x32x16_bf16 v[66:81], v[162:165], v[150:153], v[34:49]
	v_add_f32_e32 v195, v120, v195
	v_add_f32_e32 v196, v121, v196
	v_add_f32_e32 v50, v122, v50
	v_add_f32_e32 v194, v123, v194
	v_cvt_pk_bf16_f32 v160, v118, v119
	v_cvt_pk_bf16_f32 v161, v120, v121
	ds_read_b64_tr_b16 v[114:115], v200 offset:25600
	ds_read_b64_tr_b16 v[116:117], v200 offset:26112
	v_mfma_f32_32x32x16_bf16 v[82:97], v[166:169], v[138:141], v[82:97]
	v_add_f32_e32 v195, v124, v195
	v_add_f32_e32 v196, v125, v196
	v_add_f32_e32 v50, v126, v50
	v_add_f32_e32 v194, v127, v194
	v_cvt_pk_bf16_f32 v154, v122, v123
	v_cvt_pk_bf16_f32 v155, v124, v125
	ds_read_b64_tr_b16 v[118:119], v200 offset:29696
	ds_read_b64_tr_b16 v[120:121], v200 offset:30208
	v_mfma_f32_32x32x16_bf16 v[66:81], v[170:173], v[138:141], v[66:81]
	v_add_f32_e32 v195, v128, v195
	v_add_f32_e32 v196, v129, v196
	v_add_f32_e32 v50, v98, v50
	v_add_f32_e32 v194, v99, v194
	v_cvt_pk_bf16_f32 v156, v126, v127
	v_cvt_pk_bf16_f32 v157, v128, v129
	ds_read_b64_tr_b16 v[122:123], v200 offset:26624
	ds_read_b64_tr_b16 v[124:125], v200 offset:27136
	v_mfma_f32_32x32x16_bf16 v[82:97], v[174:177], v[134:137], v[82:97]
	v_add_f32_e32 v195, v100, v195
	v_add_f32_e32 v196, v101, v196
	v_add_f32_e32 v50, v102, v50
	v_add_f32_e32 v194, v103, v194
	v_cvt_pk_bf16_f32 v146, v98, v99
	v_cvt_pk_bf16_f32 v147, v100, v101
	ds_read_b64_tr_b16 v[98:99], v200 offset:30720
	ds_read_b64_tr_b16 v[100:101], v200 offset:31232
	v_mfma_f32_32x32x16_bf16 v[66:81], v[178:181], v[134:137], v[66:81]
	v_add_f32_e32 v195, v104, v195
	v_add_f32_e32 v196, v105, v196
	v_add_f32_e32 v50, v106, v50
	v_add_f32_e32 v194, v107, v194
	v_cvt_pk_bf16_f32 v148, v102, v103
	v_cvt_pk_bf16_f32 v149, v104, v105
	ds_read_b64_tr_b16 v[102:103], v200 offset:27648
	ds_read_b64_tr_b16 v[104:105], v200 offset:28160
	v_mfma_f32_32x32x16_bf16 v[82:97], v[182:185], v[130:133], v[82:97]
	v_add_f32_e32 v195, v108, v195
	v_add_f32_e32 v196, v109, v196
	v_add_f32_e32 v50, v110, v50
	v_add_f32_e32 v194, v111, v194
	v_cvt_pk_bf16_f32 v142, v106, v107
	v_cvt_pk_bf16_f32 v143, v108, v109
	ds_read_b64_tr_b16 v[106:107], v200 offset:31744
	ds_read_b64_tr_b16 v[108:109], v200 offset:32256
	v_mfma_f32_32x32x16_bf16 v[66:81], v[52:55], v[130:133], v[66:81]
	v_add_f32_e32 v195, v112, v195
	v_add_f32_e32 v196, v113, v196
	v_cvt_pk_bf16_f32 v144, v110, v111
	v_cvt_pk_bf16_f32 v145, v112, v113
	s_add_i32 s6, s76, s70
	s_mov_b32 s7, m0
	s_mov_b32 m0, s6
	s_nop 0
	global_load_lds_dwordx4 v197, s[98:99]
	s_mov_b32 m0, s7
	s_add_i32 s6, s31, s71
	s_mov_b32 s7, m0
	s_mov_b32 m0, s6
	s_nop 0
	global_load_lds_dwordx4 v197, s[100:101]
	s_mov_b32 m0, s7
	s_add_u32 s98, s98, 0x2000
	s_addc_u32 s99, s99, 0
	s_add_u32 s100, s100, 0x2000
	s_addc_u32 s101, s101, 0
	s_waitcnt lgkmcnt(14)
	v_mfma_f32_32x32x16_bf16 v[2:17], v[158:161], v[186:189], v[2:17]
	v_exp_f32_e32 v82, v82
	v_exp_f32_e32 v83, v83
	v_exp_f32_e32 v84, v84
	v_exp_f32_e32 v85, v85
	s_waitcnt lgkmcnt(12)
	v_mfma_f32_32x32x16_bf16 v[18:33], v[158:161], v[60:63], v[18:33]
	v_exp_f32_e32 v86, v86
	v_exp_f32_e32 v87, v87
	v_exp_f32_e32 v88, v88
	v_exp_f32_e32 v89, v89
	ds_read_b128 v[190:193], v202
	ds_read_b128 v[186:189], v202 offset:512
	s_waitcnt lgkmcnt(12)
	v_mfma_f32_32x32x16_bf16 v[2:17], v[154:157], v[114:117], v[2:17]
	v_exp_f32_e32 v90, v90
	v_exp_f32_e32 v91, v91
	v_exp_f32_e32 v92, v92
	v_exp_f32_e32 v93, v93
	ds_read_b128 v[182:185], v202 offset:2048
	ds_read_b128 v[178:181], v202 offset:2560
	s_waitcnt lgkmcnt(12)
	v_mfma_f32_32x32x16_bf16 v[18:33], v[154:157], v[118:121], v[18:33]
	v_exp_f32_e32 v94, v94
	v_exp_f32_e32 v95, v95
	v_exp_f32_e32 v96, v96
	v_exp_f32_e32 v97, v97
	ds_read_b128 v[174:177], v202 offset:4096
	ds_read_b128 v[170:173], v202 offset:4608
	s_waitcnt lgkmcnt(12)
	v_mfma_f32_32x32x16_bf16 v[2:17], v[146:149], v[122:125], v[2:17]
	v_exp_f32_e32 v66, v66
	v_exp_f32_e32 v67, v67
	v_exp_f32_e32 v68, v68
	v_exp_f32_e32 v69, v69
	ds_read_b128 v[166:169], v202 offset:6144
	ds_read_b128 v[162:165], v202 offset:6656
	s_waitcnt lgkmcnt(12)
	v_mfma_f32_32x32x16_bf16 v[18:33], v[146:149], v[98:101], v[18:33]
	v_exp_f32_e32 v70, v70
	v_exp_f32_e32 v71, v71
	v_exp_f32_e32 v72, v72
	v_exp_f32_e32 v73, v73
	s_waitcnt lgkmcnt(10)
	v_mfma_f32_32x32x16_bf16 v[2:17], v[142:145], v[102:105], v[2:17]
	v_exp_f32_e32 v74, v74
	v_exp_f32_e32 v75, v75
	v_exp_f32_e32 v76, v76
	v_exp_f32_e32 v77, v77
	s_waitcnt lgkmcnt(8)
	v_mfma_f32_32x32x16_bf16 v[18:33], v[142:145], v[106:109], v[18:33]
	v_exp_f32_e32 v78, v78
	v_exp_f32_e32 v79, v79
	v_exp_f32_e32 v80, v80
	v_exp_f32_e32 v81, v81
	s_add_i32 s6, s31, 0x2000
	s_cmpk_lg_i32 s31, 0x4000
	s_mov_b32 s24, s76
	s_cselect_b32 s76, s6, 0
	s_add_i32 s26, s26, 2
	s_cmp_ge_i32 s26, s91
	s_cbranch_scc1 .Lattn_exit
	s_waitcnt vmcnt(2) lgkmcnt(0)
	s_barrier
; #define WAIT_BAR(N) asm volatile("s_waitcnt vmcnt(" #N ") lgkmcnt(0)\n\ts_barrier":::"memory")
;   #define RESC() do{ if(resc){ asm volatile("s_waitcnt lgkmcnt(0)":::"memory"); \
;       _Pragma("unroll") for(int d_=0;d_<2;++d_) _Pragma("unroll") for(int r=0;r<16;++r)o[d_][r]*=wsf[crow(r,hi)]; } }while(0)
;   #define ROT() do{sl_prev=sl_cur;sl_cur=sl_next;sl_next=(sl_next==(NSLOT-1)*SLOTB)?0:sl_next+SLOTB;}while(0)
; template<int THRL> __device__ __forceinline__ void attn_unit(const bf16*Qu,const bf16*__restrict__ Kh,const bf16*__restrict__ Vh,bf16*Ou,const int NT,const float shift,char*shm){
;     ...
;   int t=1;
;     ...
;   for(;t+5<NT;t+=2){
;     STEP(pB0,pB1,pA0,pA1,t,true,true,true);     WAIT_BAR(2); RESC(); ROT();
;     STEP(pA0,pA1,pB0,pB1,t+1,true,true,true);   WAIT_BAR(2); RESC(); ROT();
.Lattn_cpB:
	s_mov_b32 s4, s76
	s_mov_b32 s5, s26
	s_mov_b32 s25, s31
	ds_read_b64_tr_b16 v[52:53], v201 offset:24576
	ds_read_b64_tr_b16 v[54:55], v201 offset:25088
	v_mfma_f32_32x32x16_bf16 v[114:129], v[190:193], v[150:153], v[34:49]
	v_add_f32_e32 v50, v82, v50
	v_add_f32_e32 v194, v83, v194
	v_add_f32_e32 v195, v84, v195
	v_add_f32_e32 v196, v85, v196
	v_add_f32_e32 v50, v86, v50
	v_add_f32_e32 v194, v87, v194
	v_cvt_pk_bf16_f32 v158, v82, v83
	v_cvt_pk_bf16_f32 v159, v84, v85
	ds_read_b64_tr_b16 v[60:61], v201 offset:28672
	ds_read_b64_tr_b16 v[62:63], v201 offset:29184
	v_mfma_f32_32x32x16_bf16 v[98:113], v[186:189], v[150:153], v[34:49]
	v_add_f32_e32 v195, v88, v195
	v_add_f32_e32 v196, v89, v196
	v_add_f32_e32 v50, v90, v50
	v_add_f32_e32 v194, v91, v194
	v_cvt_pk_bf16_f32 v160, v86, v87
	v_cvt_pk_bf16_f32 v161, v88, v89
	ds_read_b64_tr_b16 v[82:83], v201 offset:25600
	ds_read_b64_tr_b16 v[84:85], v201 offset:26112
	v_mfma_f32_32x32x16_bf16 v[114:129], v[182:185], v[138:141], v[114:129]
	v_add_f32_e32 v195, v92, v195
	v_add_f32_e32 v196, v93, v196
	v_add_f32_e32 v50, v94, v50
	v_add_f32_e32 v194, v95, v194
	v_cvt_pk_bf16_f32 v154, v90, v91
	v_cvt_pk_bf16_f32 v155, v92, v93
	ds_read_b64_tr_b16 v[86:87], v201 offset:29696
	ds_read_b64_tr_b16 v[88:89], v201 offset:30208
	v_mfma_f32_32x32x16_bf16 v[98:113], v[178:181], v[138:141], v[98:113]
	v_add_f32_e32 v195, v96, v195
	v_add_f32_e32 v196, v97, v196
	v_add_f32_e32 v50, v66, v50
	v_add_f32_e32 v194, v67, v194
	v_cvt_pk_bf16_f32 v156, v94, v95
	v_cvt_pk_bf16_f32 v157, v96, v97
	ds_read_b64_tr_b16 v[90:91], v201 offset:26624
	ds_read_b64_tr_b16 v[92:93], v201 offset:27136
	v_mfma_f32_32x32x16_bf16 v[114:129], v[174:177], v[134:137], v[114:129]
	v_add_f32_e32 v195, v68, v195
	v_add_f32_e32 v196, v69, v196
	v_add_f32_e32 v50, v70, v50
	v_add_f32_e32 v194, v71, v194
	v_cvt_pk_bf16_f32 v146, v66, v67
	v_cvt_pk_bf16_f32 v147, v68, v69
	ds_read_b64_tr_b16 v[64:65], v201 offset:30720
	ds_read_b64_tr_b16 v[66:67], v201 offset:31232
	v_mfma_f32_32x32x16_bf16 v[98:113], v[170:173], v[134:137], v[98:113]
	v_add_f32_e32 v195, v72, v195
	v_add_f32_e32 v196, v73, v196
	v_add_f32_e32 v50, v74, v50
	v_add_f32_e32 v194, v75, v194
	v_cvt_pk_bf16_f32 v148, v70, v71
	v_cvt_pk_bf16_f32 v149, v72, v73
	ds_read_b64_tr_b16 v[68:69], v201 offset:27648
	ds_read_b64_tr_b16 v[70:71], v201 offset:28160
	v_mfma_f32_32x32x16_bf16 v[114:129], v[166:169], v[130:133], v[114:129]
	v_add_f32_e32 v195, v76, v195
	v_add_f32_e32 v196, v77, v196
	v_add_f32_e32 v50, v78, v50
	v_add_f32_e32 v194, v79, v194
	v_cvt_pk_bf16_f32 v142, v74, v75
	v_cvt_pk_bf16_f32 v143, v76, v77
	ds_read_b64_tr_b16 v[72:73], v201 offset:31744
	ds_read_b64_tr_b16 v[74:75], v201 offset:32256
	v_mfma_f32_32x32x16_bf16 v[98:113], v[162:165], v[130:133], v[98:113]
	v_add_f32_e32 v195, v80, v195
	v_add_f32_e32 v196, v81, v196
	v_cvt_pk_bf16_f32 v144, v78, v79
	v_cvt_pk_bf16_f32 v145, v80, v81
	s_add_i32 s6, s31, s70
	s_mov_b32 s7, m0
	s_mov_b32 m0, s6
	s_nop 0
	global_load_lds_dwordx4 v197, s[98:99]
	s_mov_b32 m0, s7
	s_add_i32 s6, s76, s71
	s_mov_b32 s7, m0
	s_mov_b32 m0, s6
	s_nop 0
	global_load_lds_dwordx4 v197, s[100:101]
	s_mov_b32 m0, s7
	s_add_u32 s98, s98, 0x2000
	s_addc_u32 s99, s99, 0
	s_add_u32 s100, s100, 0x2000
	s_addc_u32 s101, s101, 0
	s_waitcnt lgkmcnt(14)
	v_mfma_f32_32x32x16_bf16 v[2:17], v[158:161], v[52:55], v[2:17]
	v_exp_f32_e32 v114, v114
	v_exp_f32_e32 v115, v115
	v_exp_f32_e32 v116, v116
	v_exp_f32_e32 v117, v117
	s_waitcnt lgkmcnt(12)
	v_mfma_f32_32x32x16_bf16 v[18:33], v[158:161], v[60:63], v[18:33]
	v_exp_f32_e32 v118, v118
	v_exp_f32_e32 v119, v119
	v_exp_f32_e32 v120, v120
	v_exp_f32_e32 v121, v121
	ds_read_b128 v[60:63], v203
	ds_read_b128 v[162:165], v203 offset:512
	s_waitcnt lgkmcnt(12)
	v_mfma_f32_32x32x16_bf16 v[2:17], v[154:157], v[82:85], v[2:17]
	v_exp_f32_e32 v122, v122
	v_exp_f32_e32 v123, v123
	v_exp_f32_e32 v124, v124
	v_exp_f32_e32 v125, v125
	ds_read_b128 v[166:169], v203 offset:2048
	ds_read_b128 v[170:173], v203 offset:2560
	s_waitcnt lgkmcnt(12)
	v_mfma_f32_32x32x16_bf16 v[18:33], v[154:157], v[86:89], v[18:33]
	v_exp_f32_e32 v126, v126
	v_exp_f32_e32 v127, v127
	v_exp_f32_e32 v128, v128
	v_exp_f32_e32 v129, v129
	ds_read_b128 v[174:177], v203 offset:4096
	ds_read_b128 v[178:181], v203 offset:4608
	s_waitcnt lgkmcnt(12)
	v_mfma_f32_32x32x16_bf16 v[2:17], v[146:149], v[90:93], v[2:17]
	v_exp_f32_e32 v98, v98
	v_exp_f32_e32 v99, v99
	v_exp_f32_e32 v100, v100
	v_exp_f32_e32 v101, v101
	ds_read_b128 v[182:185], v203 offset:6144
	ds_read_b128 v[52:55], v203 offset:6656
	s_waitcnt lgkmcnt(12)
	v_mfma_f32_32x32x16_bf16 v[18:33], v[146:149], v[64:67], v[18:33]
	v_exp_f32_e32 v102, v102
	v_exp_f32_e32 v103, v103
	v_exp_f32_e32 v104, v104
	v_exp_f32_e32 v105, v105
	s_waitcnt lgkmcnt(10)
	v_mfma_f32_32x32x16_bf16 v[2:17], v[142:145], v[68:71], v[2:17]
	v_exp_f32_e32 v106, v106
	v_exp_f32_e32 v107, v107
	v_exp_f32_e32 v108, v108
	v_exp_f32_e32 v109, v109
	s_waitcnt lgkmcnt(8)
	v_mfma_f32_32x32x16_bf16 v[18:33], v[142:145], v[72:75], v[18:33]
	v_exp_f32_e32 v110, v110
	v_exp_f32_e32 v111, v111
	v_exp_f32_e32 v112, v112
	v_exp_f32_e32 v113, v113
	s_waitcnt vmcnt(2) lgkmcnt(0)
	s_barrier
; #define WAIT_BAR(N) asm volatile("s_waitcnt vmcnt(" #N ") lgkmcnt(0)\n\ts_barrier":::"memory")
;   #define RESC() do{ if(resc){ asm volatile("s_waitcnt lgkmcnt(0)":::"memory"); \
;       _Pragma("unroll") for(int d_=0;d_<2;++d_) _Pragma("unroll") for(int r=0;r<16;++r)o[d_][r]*=wsf[crow(r,hi)]; } }while(0)
;   #define ROT() do{sl_prev=sl_cur;sl_cur=sl_next;sl_next=(sl_next==(NSLOT-1)*SLOTB)?0:sl_next+SLOTB;}while(0)
; template<int THRL> __device__ __forceinline__ void attn_unit(const bf16*Qu,const bf16*__restrict__ Kh,const bf16*__restrict__ Vh,bf16*Ou,const int NT,const float shift,char*shm){
;     ...
;   int t=1;
;     ...
;   for(;t+5<NT;t+=2){
;     STEP(pB0,pB1,pA0,pA1,t,true,true,true);     WAIT_BAR(2); RESC(); ROT();
;     STEP(pA0,pA1,pB0,pB1,t+1,true,true,true);   WAIT_BAR(2); RESC(); ROT();
;   }
	s_add_i32 s6, s76, 0x2000
	s_cmpk_lg_i32 s76, 0x4000
	s_cselect_b32 s31, s6, 0
	ds_read_b64_tr_b16 v[186:187], v199 offset:24576
	ds_read_b64_tr_b16 v[188:189], v199 offset:25088
	v_mfma_f32_32x32x16_bf16 v[82:97], v[60:63], v[150:153], v[34:49]
	v_add_f32_e32 v50, v114, v50
	v_add_f32_e32 v194, v115, v194
	v_add_f32_e32 v195, v116, v195
	v_add_f32_e32 v196, v117, v196
	v_add_f32_e32 v50, v118, v50
	v_add_f32_e32 v194, v119, v194
	v_cvt_pk_bf16_f32 v158, v114, v115
	v_cvt_pk_bf16_f32 v159, v116, v117
	ds_read_b64_tr_b16 v[60:61], v199 offset:28672
	ds_read_b64_tr_b16 v[62:63], v199 offset:29184
	v_mfma_f32_32x32x16_bf16 v[66:81], v[162:165], v[150:153], v[34:49]
	v_add_f32_e32 v195, v120, v195
	v_add_f32_e32 v196, v121, v196
	v_add_f32_e32 v50, v122, v50
	v_add_f32_e32 v194, v123, v194
	v_cvt_pk_bf16_f32 v160, v118, v119
	v_cvt_pk_bf16_f32 v161, v120, v121
	ds_read_b64_tr_b16 v[114:115], v199 offset:25600
	ds_read_b64_tr_b16 v[116:117], v199 offset:26112
	v_mfma_f32_32x32x16_bf16 v[82:97], v[166:169], v[138:141], v[82:97]
	v_add_f32_e32 v195, v124, v195
	v_add_f32_e32 v196, v125, v196
	v_add_f32_e32 v50, v126, v50
	v_add_f32_e32 v194, v127, v194
	v_cvt_pk_bf16_f32 v154, v122, v123
	v_cvt_pk_bf16_f32 v155, v124, v125
	ds_read_b64_tr_b16 v[118:119], v199 offset:29696
	ds_read_b64_tr_b16 v[120:121], v199 offset:30208
	v_mfma_f32_32x32x16_bf16 v[66:81], v[170:173], v[138:141], v[66:81]
	v_add_f32_e32 v195, v128, v195
	v_add_f32_e32 v196, v129, v196
	v_add_f32_e32 v50, v98, v50
	v_add_f32_e32 v194, v99, v194
	v_cvt_pk_bf16_f32 v156, v126, v127
	v_cvt_pk_bf16_f32 v157, v128, v129
	ds_read_b64_tr_b16 v[122:123], v199 offset:26624
	ds_read_b64_tr_b16 v[124:125], v199 offset:27136
	v_mfma_f32_32x32x16_bf16 v[82:97], v[174:177], v[134:137], v[82:97]
	v_add_f32_e32 v195, v100, v195
	v_add_f32_e32 v196, v101, v196
	v_add_f32_e32 v50, v102, v50
	v_add_f32_e32 v194, v103, v194
	v_cvt_pk_bf16_f32 v146, v98, v99
	v_cvt_pk_bf16_f32 v147, v100, v101
	ds_read_b64_tr_b16 v[98:99], v199 offset:30720
	ds_read_b64_tr_b16 v[100:101], v199 offset:31232
	v_mfma_f32_32x32x16_bf16 v[66:81], v[178:181], v[134:137], v[66:81]
	v_add_f32_e32 v195, v104, v195
	v_add_f32_e32 v196, v105, v196
	v_add_f32_e32 v50, v106, v50
	v_add_f32_e32 v194, v107, v194
	v_cvt_pk_bf16_f32 v148, v102, v103
	v_cvt_pk_bf16_f32 v149, v104, v105
	ds_read_b64_tr_b16 v[102:103], v199 offset:27648
	ds_read_b64_tr_b16 v[104:105], v199 offset:28160
	v_mfma_f32_32x32x16_bf16 v[82:97], v[182:185], v[130:133], v[82:97]
	v_add_f32_e32 v195, v108, v195
	v_add_f32_e32 v196, v109, v196
	v_add_f32_e32 v50, v110, v50
	v_add_f32_e32 v194, v111, v194
	v_cvt_pk_bf16_f32 v142, v106, v107
	v_cvt_pk_bf16_f32 v143, v108, v109
	ds_read_b64_tr_b16 v[106:107], v199 offset:31744
	ds_read_b64_tr_b16 v[108:109], v199 offset:32256
	v_mfma_f32_32x32x16_bf16 v[66:81], v[52:55], v[130:133], v[66:81]
	v_add_f32_e32 v195, v112, v195
	v_add_f32_e32 v196, v113, v196
	v_cvt_pk_bf16_f32 v144, v110, v111
	v_cvt_pk_bf16_f32 v145, v112, v113
	s_add_i32 s6, s76, s70
	s_mov_b32 s7, m0
	s_mov_b32 m0, s6
	s_nop 0
	global_load_lds_dwordx4 v197, s[98:99]
	s_mov_b32 m0, s7
	s_add_i32 s6, s31, s71
	s_mov_b32 s7, m0
	s_mov_b32 m0, s6
	s_nop 0
	global_load_lds_dwordx4 v197, s[100:101]
	s_mov_b32 m0, s7
	s_add_u32 s98, s98, 0x2000
	s_addc_u32 s99, s99, 0
	s_add_u32 s100, s100, 0x2000
	s_addc_u32 s101, s101, 0
	s_waitcnt lgkmcnt(14)
	v_mfma_f32_32x32x16_bf16 v[2:17], v[158:161], v[186:189], v[2:17]
	v_exp_f32_e32 v82, v82
	v_exp_f32_e32 v83, v83
	v_exp_f32_e32 v84, v84
	v_exp_f32_e32 v85, v85
	s_waitcnt lgkmcnt(12)
	v_mfma_f32_32x32x16_bf16 v[18:33], v[158:161], v[60:63], v[18:33]
	v_exp_f32_e32 v86, v86
	v_exp_f32_e32 v87, v87
	v_exp_f32_e32 v88, v88
	v_exp_f32_e32 v89, v89
	ds_read_b128 v[190:193], v204
	ds_read_b128 v[186:189], v204 offset:512
	s_waitcnt lgkmcnt(12)
	v_mfma_f32_32x32x16_bf16 v[2:17], v[154:157], v[114:117], v[2:17]
	v_exp_f32_e32 v90, v90
	v_exp_f32_e32 v91, v91
	v_exp_f32_e32 v92, v92
	v_exp_f32_e32 v93, v93
	ds_read_b128 v[182:185], v204 offset:2048
	ds_read_b128 v[178:181], v204 offset:2560
	s_waitcnt lgkmcnt(12)
	v_mfma_f32_32x32x16_bf16 v[18:33], v[154:157], v[118:121], v[18:33]
	v_exp_f32_e32 v94, v94
	v_exp_f32_e32 v95, v95
	v_exp_f32_e32 v96, v96
	v_exp_f32_e32 v97, v97
	ds_read_b128 v[174:177], v204 offset:4096
	ds_read_b128 v[170:173], v204 offset:4608
	s_waitcnt lgkmcnt(12)
	v_mfma_f32_32x32x16_bf16 v[2:17], v[146:149], v[122:125], v[2:17]
	v_exp_f32_e32 v66, v66
	v_exp_f32_e32 v67, v67
	v_exp_f32_e32 v68, v68
	v_exp_f32_e32 v69, v69
	ds_read_b128 v[166:169], v204 offset:6144
	ds_read_b128 v[162:165], v204 offset:6656
	s_waitcnt lgkmcnt(12)
	v_mfma_f32_32x32x16_bf16 v[18:33], v[146:149], v[98:101], v[18:33]
	v_exp_f32_e32 v70, v70
	v_exp_f32_e32 v71, v71
	v_exp_f32_e32 v72, v72
	v_exp_f32_e32 v73, v73
	s_waitcnt lgkmcnt(10)
	v_mfma_f32_32x32x16_bf16 v[2:17], v[142:145], v[102:105], v[2:17]
	v_exp_f32_e32 v74, v74
	v_exp_f32_e32 v75, v75
	v_exp_f32_e32 v76, v76
	v_exp_f32_e32 v77, v77
	s_waitcnt lgkmcnt(8)
	v_mfma_f32_32x32x16_bf16 v[18:33], v[142:145], v[106:109], v[18:33]
	v_exp_f32_e32 v78, v78
	v_exp_f32_e32 v79, v79
	v_exp_f32_e32 v80, v80
	v_exp_f32_e32 v81, v81
	s_add_i32 s6, s31, 0x2000
	s_cmpk_lg_i32 s31, 0x4000
	s_mov_b32 s24, s76
	s_cselect_b32 s76, s6, 0
	s_add_i32 s26, s26, 2
	s_cmp_ge_i32 s26, s91
	s_cbranch_scc1 .Lattn_exit
	s_waitcnt vmcnt(2) lgkmcnt(0)
	s_barrier
; #define WAIT_BAR(N) asm volatile("s_waitcnt vmcnt(" #N ") lgkmcnt(0)\n\ts_barrier":::"memory")
;   #define RESC() do{ if(resc){ asm volatile("s_waitcnt lgkmcnt(0)":::"memory"); \
;       _Pragma("unroll") for(int d_=0;d_<2;++d_) _Pragma("unroll") for(int r=0;r<16;++r)o[d_][r]*=wsf[crow(r,hi)]; } }while(0)
;   #define ROT() do{sl_prev=sl_cur;sl_cur=sl_next;sl_next=(sl_next==(NSLOT-1)*SLOTB)?0:sl_next+SLOTB;}while(0)
; template<int THRL> __device__ __forceinline__ void attn_unit(const bf16*Qu,const bf16*__restrict__ Kh,const bf16*__restrict__ Vh,bf16*Ou,const int NT,const float shift,char*shm){
;     ...
;   int t=1;
;     ...
;   for(;t+5<NT;t+=2){
;     STEP(pB0,pB1,pA0,pA1,t,true,true,true);     WAIT_BAR(2); RESC(); ROT();
;     STEP(pA0,pA1,pB0,pB1,t+1,true,true,true);   WAIT_BAR(2); RESC(); ROT();
.Lattn_cpC:
	s_mov_b32 s4, s76
	s_mov_b32 s5, s26
	s_mov_b32 s25, s31
	ds_read_b64_tr_b16 v[52:53], v200 offset:24576
	ds_read_b64_tr_b16 v[54:55], v200 offset:25088
	v_mfma_f32_32x32x16_bf16 v[114:129], v[190:193], v[150:153], v[34:49]
	v_add_f32_e32 v50, v82, v50
	v_add_f32_e32 v194, v83, v194
	v_add_f32_e32 v195, v84, v195
	v_add_f32_e32 v196, v85, v196
	v_add_f32_e32 v50, v86, v50
	v_add_f32_e32 v194, v87, v194
	v_cvt_pk_bf16_f32 v158, v82, v83
	v_cvt_pk_bf16_f32 v159, v84, v85
	ds_read_b64_tr_b16 v[60:61], v200 offset:28672
	ds_read_b64_tr_b16 v[62:63], v200 offset:29184
	v_mfma_f32_32x32x16_bf16 v[98:113], v[186:189], v[150:153], v[34:49]
	v_add_f32_e32 v195, v88, v195
	v_add_f32_e32 v196, v89, v196
	v_add_f32_e32 v50, v90, v50
	v_add_f32_e32 v194, v91, v194
	v_cvt_pk_bf16_f32 v160, v86, v87
	v_cvt_pk_bf16_f32 v161, v88, v89
	ds_read_b64_tr_b16 v[82:83], v200 offset:25600
	ds_read_b64_tr_b16 v[84:85], v200 offset:26112
	v_mfma_f32_32x32x16_bf16 v[114:129], v[182:185], v[138:141], v[114:129]
	v_add_f32_e32 v195, v92, v195
	v_add_f32_e32 v196, v93, v196
	v_add_f32_e32 v50, v94, v50
	v_add_f32_e32 v194, v95, v194
	v_cvt_pk_bf16_f32 v154, v90, v91
	v_cvt_pk_bf16_f32 v155, v92, v93
	ds_read_b64_tr_b16 v[86:87], v200 offset:29696
	ds_read_b64_tr_b16 v[88:89], v200 offset:30208
	v_mfma_f32_32x32x16_bf16 v[98:113], v[178:181], v[138:141], v[98:113]
	v_add_f32_e32 v195, v96, v195
	v_add_f32_e32 v196, v97, v196
	v_add_f32_e32 v50, v66, v50
	v_add_f32_e32 v194, v67, v194
	v_cvt_pk_bf16_f32 v156, v94, v95
	v_cvt_pk_bf16_f32 v157, v96, v97
	ds_read_b64_tr_b16 v[90:91], v200 offset:26624
	ds_read_b64_tr_b16 v[92:93], v200 offset:27136
	v_mfma_f32_32x32x16_bf16 v[114:129], v[174:177], v[134:137], v[114:129]
	v_add_f32_e32 v195, v68, v195
	v_add_f32_e32 v196, v69, v196
	v_add_f32_e32 v50, v70, v50
	v_add_f32_e32 v194, v71, v194
	v_cvt_pk_bf16_f32 v146, v66, v67
	v_cvt_pk_bf16_f32 v147, v68, v69
	ds_read_b64_tr_b16 v[64:65], v200 offset:30720
	ds_read_b64_tr_b16 v[66:67], v200 offset:31232
	v_mfma_f32_32x32x16_bf16 v[98:113], v[170:173], v[134:137], v[98:113]
	v_add_f32_e32 v195, v72, v195
	v_add_f32_e32 v196, v73, v196
	v_add_f32_e32 v50, v74, v50
	v_add_f32_e32 v194, v75, v194
	v_cvt_pk_bf16_f32 v148, v70, v71
	v_cvt_pk_bf16_f32 v149, v72, v73
	ds_read_b64_tr_b16 v[68:69], v200 offset:27648
	ds_read_b64_tr_b16 v[70:71], v200 offset:28160
	v_mfma_f32_32x32x16_bf16 v[114:129], v[166:169], v[130:133], v[114:129]
	v_add_f32_e32 v195, v76, v195
	v_add_f32_e32 v196, v77, v196
	v_add_f32_e32 v50, v78, v50
	v_add_f32_e32 v194, v79, v194
	v_cvt_pk_bf16_f32 v142, v74, v75
	v_cvt_pk_bf16_f32 v143, v76, v77
	ds_read_b64_tr_b16 v[72:73], v200 offset:31744
	ds_read_b64_tr_b16 v[74:75], v200 offset:32256
	v_mfma_f32_32x32x16_bf16 v[98:113], v[162:165], v[130:133], v[98:113]
	v_add_f32_e32 v195, v80, v195
	v_add_f32_e32 v196, v81, v196
	v_cvt_pk_bf16_f32 v144, v78, v79
	v_cvt_pk_bf16_f32 v145, v80, v81
	s_add_i32 s6, s31, s70
	s_mov_b32 s7, m0
	s_mov_b32 m0, s6
	s_nop 0
	global_load_lds_dwordx4 v197, s[98:99]
	s_mov_b32 m0, s7
	s_add_i32 s6, s76, s71
	s_mov_b32 s7, m0
	s_mov_b32 m0, s6
	s_nop 0
	global_load_lds_dwordx4 v197, s[100:101]
	s_mov_b32 m0, s7
	s_add_u32 s98, s98, 0x2000
	s_addc_u32 s99, s99, 0
	s_add_u32 s100, s100, 0x2000
	s_addc_u32 s101, s101, 0
	s_waitcnt lgkmcnt(14)
	v_mfma_f32_32x32x16_bf16 v[2:17], v[158:161], v[52:55], v[2:17]
	v_exp_f32_e32 v114, v114
	v_exp_f32_e32 v115, v115
	v_exp_f32_e32 v116, v116
	v_exp_f32_e32 v117, v117
	s_waitcnt lgkmcnt(12)
	v_mfma_f32_32x32x16_bf16 v[18:33], v[158:161], v[60:63], v[18:33]
	v_exp_f32_e32 v118, v118
	v_exp_f32_e32 v119, v119
	v_exp_f32_e32 v120, v120
	v_exp_f32_e32 v121, v121
	ds_read_b128 v[60:63], v202
	ds_read_b128 v[162:165], v202 offset:512
	s_waitcnt lgkmcnt(12)
	v_mfma_f32_32x32x16_bf16 v[2:17], v[154:157], v[82:85], v[2:17]
	v_exp_f32_e32 v122, v122
	v_exp_f32_e32 v123, v123
	v_exp_f32_e32 v124, v124
	v_exp_f32_e32 v125, v125
	ds_read_b128 v[166:169], v202 offset:2048
	ds_read_b128 v[170:173], v202 offset:2560
	s_waitcnt lgkmcnt(12)
	v_mfma_f32_32x32x16_bf16 v[18:33], v[154:157], v[86:89], v[18:33]
	v_exp_f32_e32 v126, v126
	v_exp_f32_e32 v127, v127
	v_exp_f32_e32 v128, v128
	v_exp_f32_e32 v129, v129
	ds_read_b128 v[174:177], v202 offset:4096
	ds_read_b128 v[178:181], v202 offset:4608
	s_waitcnt lgkmcnt(12)
	v_mfma_f32_32x32x16_bf16 v[2:17], v[146:149], v[90:93], v[2:17]
	v_exp_f32_e32 v98, v98
	v_exp_f32_e32 v99, v99
	v_exp_f32_e32 v100, v100
	v_exp_f32_e32 v101, v101
	ds_read_b128 v[182:185], v202 offset:6144
	ds_read_b128 v[52:55], v202 offset:6656
	s_waitcnt lgkmcnt(12)
	v_mfma_f32_32x32x16_bf16 v[18:33], v[146:149], v[64:67], v[18:33]
	v_exp_f32_e32 v102, v102
	v_exp_f32_e32 v103, v103
	v_exp_f32_e32 v104, v104
	v_exp_f32_e32 v105, v105
	s_waitcnt lgkmcnt(10)
	v_mfma_f32_32x32x16_bf16 v[2:17], v[142:145], v[68:71], v[2:17]
	v_exp_f32_e32 v106, v106
	v_exp_f32_e32 v107, v107
	v_exp_f32_e32 v108, v108
	v_exp_f32_e32 v109, v109
	s_waitcnt lgkmcnt(8)
	v_mfma_f32_32x32x16_bf16 v[18:33], v[142:145], v[72:75], v[18:33]
	v_exp_f32_e32 v110, v110
	v_exp_f32_e32 v111, v111
	v_exp_f32_e32 v112, v112
	v_exp_f32_e32 v113, v113
	s_waitcnt vmcnt(2) lgkmcnt(0)
	s_barrier
; #define WAIT_BAR(N) asm volatile("s_waitcnt vmcnt(" #N ") lgkmcnt(0)\n\ts_barrier":::"memory")
;   #define RESC() do{ if(resc){ asm volatile("s_waitcnt lgkmcnt(0)":::"memory"); \
;       _Pragma("unroll") for(int d_=0;d_<2;++d_) _Pragma("unroll") for(int r=0;r<16;++r)o[d_][r]*=wsf[crow(r,hi)]; } }while(0)
;   #define ROT() do{sl_prev=sl_cur;sl_cur=sl_next;sl_next=(sl_next==(NSLOT-1)*SLOTB)?0:sl_next+SLOTB;}while(0)
; template<int THRL> __device__ __forceinline__ void attn_unit(const bf16*Qu,const bf16*__restrict__ Kh,const bf16*__restrict__ Vh,bf16*Ou,const int NT,const float shift,char*shm){
;     ...
;   int t=1;
;     ...
;   for(;t+5<NT;t+=2){
;     STEP(pB0,pB1,pA0,pA1,t,true,true,true);     WAIT_BAR(2); RESC(); ROT();
	s_add_i32 s6, s76, 0x2000
	s_cmpk_lg_i32 s76, 0x4000
	s_cselect_b32 s31, s6, 0
	ds_read_b64_tr_b16 v[186:187], v201 offset:24576
	ds_read_b64_tr_b16 v[188:189], v201 offset:25088
	v_mfma_f32_32x32x16_bf16 v[82:97], v[60:63], v[150:153], v[34:49]
	v_add_f32_e32 v50, v114, v50
	v_add_f32_e32 v194, v115, v194
	v_add_f32_e32 v195, v116, v195
	v_add_f32_e32 v196, v117, v196
	v_add_f32_e32 v50, v118, v50
	v_add_f32_e32 v194, v119, v194
	v_cvt_pk_bf16_f32 v158, v114, v115
	v_cvt_pk_bf16_f32 v159, v116, v117
	ds_read_b64_tr_b16 v[60:61], v201 offset:28672
	ds_read_b64_tr_b16 v[62:63], v201 offset:29184
	v_mfma_f32_32x32x16_bf16 v[66:81], v[162:165], v[150:153], v[34:49]
	v_add_f32_e32 v195, v120, v195
	v_add_f32_e32 v196, v121, v196
	v_add_f32_e32 v50, v122, v50
	v_add_f32_e32 v194, v123, v194
	v_cvt_pk_bf16_f32 v160, v118, v119
	v_cvt_pk_bf16_f32 v161, v120, v121
	ds_read_b64_tr_b16 v[114:115], v201 offset:25600
	ds_read_b64_tr_b16 v[116:117], v201 offset:26112
	v_mfma_f32_32x32x16_bf16 v[82:97], v[166:169], v[138:141], v[82:97]
	v_add_f32_e32 v195, v124, v195
	v_add_f32_e32 v196, v125, v196
	v_add_f32_e32 v50, v126, v50
	v_add_f32_e32 v194, v127, v194
	v_cvt_pk_bf16_f32 v154, v122, v123
	v_cvt_pk_bf16_f32 v155, v124, v125
	ds_read_b64_tr_b16 v[118:119], v201 offset:29696
	ds_read_b64_tr_b16 v[120:121], v201 offset:30208
	v_mfma_f32_32x32x16_bf16 v[66:81], v[170:173], v[138:141], v[66:81]
	v_add_f32_e32 v195, v128, v195
	v_add_f32_e32 v196, v129, v196
	v_add_f32_e32 v50, v98, v50
	v_add_f32_e32 v194, v99, v194
	v_cvt_pk_bf16_f32 v156, v126, v127
	v_cvt_pk_bf16_f32 v157, v128, v129
	ds_read_b64_tr_b16 v[122:123], v201 offset:26624
	ds_read_b64_tr_b16 v[124:125], v201 offset:27136
	v_mfma_f32_32x32x16_bf16 v[82:97], v[174:177], v[134:137], v[82:97]
	v_add_f32_e32 v195, v100, v195
	v_add_f32_e32 v196, v101, v196
	v_add_f32_e32 v50, v102, v50
	v_add_f32_e32 v194, v103, v194
	v_cvt_pk_bf16_f32 v146, v98, v99
	v_cvt_pk_bf16_f32 v147, v100, v101
	ds_read_b64_tr_b16 v[98:99], v201 offset:30720
	ds_read_b64_tr_b16 v[100:101], v201 offset:31232
	v_mfma_f32_32x32x16_bf16 v[66:81], v[178:181], v[134:137], v[66:81]
	v_add_f32_e32 v195, v104, v195
	v_add_f32_e32 v196, v105, v196
	v_add_f32_e32 v50, v106, v50
	v_add_f32_e32 v194, v107, v194
	v_cvt_pk_bf16_f32 v148, v102, v103
	v_cvt_pk_bf16_f32 v149, v104, v105
	ds_read_b64_tr_b16 v[102:103], v201 offset:27648
	ds_read_b64_tr_b16 v[104:105], v201 offset:28160
	v_mfma_f32_32x32x16_bf16 v[82:97], v[182:185], v[130:133], v[82:97]
	v_add_f32_e32 v195, v108, v195
	v_add_f32_e32 v196, v109, v196
	v_add_f32_e32 v50, v110, v50
	v_add_f32_e32 v194, v111, v194
	v_cvt_pk_bf16_f32 v142, v106, v107
	v_cvt_pk_bf16_f32 v143, v108, v109
	ds_read_b64_tr_b16 v[106:107], v201 offset:31744
	ds_read_b64_tr_b16 v[108:109], v201 offset:32256
	v_mfma_f32_32x32x16_bf16 v[66:81], v[52:55], v[130:133], v[66:81]
	v_add_f32_e32 v195, v112, v195
	v_add_f32_e32 v196, v113, v196
	v_cvt_pk_bf16_f32 v144, v110, v111
	v_cvt_pk_bf16_f32 v145, v112, v113
	s_add_i32 s6, s76, s70
	s_mov_b32 s7, m0
	s_mov_b32 m0, s6
	s_nop 0
	global_load_lds_dwordx4 v197, s[98:99]
	s_mov_b32 m0, s7
	s_add_i32 s6, s31, s71
	s_mov_b32 s7, m0
	s_mov_b32 m0, s6
	s_nop 0
	global_load_lds_dwordx4 v197, s[100:101]
	s_mov_b32 m0, s7
	s_add_u32 s98, s98, 0x2000
	s_addc_u32 s99, s99, 0
	s_add_u32 s100, s100, 0x2000
	s_addc_u32 s101, s101, 0
	s_waitcnt lgkmcnt(14)
	v_mfma_f32_32x32x16_bf16 v[2:17], v[158:161], v[186:189], v[2:17]
	v_exp_f32_e32 v82, v82
	v_exp_f32_e32 v83, v83
	v_exp_f32_e32 v84, v84
	v_exp_f32_e32 v85, v85
	s_waitcnt lgkmcnt(12)
	v_mfma_f32_32x32x16_bf16 v[18:33], v[158:161], v[60:63], v[18:33]
	v_exp_f32_e32 v86, v86
	v_exp_f32_e32 v87, v87
	v_exp_f32_e32 v88, v88
	v_exp_f32_e32 v89, v89
	ds_read_b128 v[190:193], v203
	ds_read_b128 v[186:189], v203 offset:512
	s_waitcnt lgkmcnt(12)
	v_mfma_f32_32x32x16_bf16 v[2:17], v[154:157], v[114:117], v[2:17]
	v_exp_f32_e32 v90, v90
	v_exp_f32_e32 v91, v91
	v_exp_f32_e32 v92, v92
	v_exp_f32_e32 v93, v93
	ds_read_b128 v[182:185], v203 offset:2048
	ds_read_b128 v[178:181], v203 offset:2560
	s_waitcnt lgkmcnt(12)
	v_mfma_f32_32x32x16_bf16 v[18:33], v[154:157], v[118:121], v[18:33]
	v_exp_f32_e32 v94, v94
	v_exp_f32_e32 v95, v95
	v_exp_f32_e32 v96, v96
	v_exp_f32_e32 v97, v97
	ds_read_b128 v[174:177], v203 offset:4096
	ds_read_b128 v[170:173], v203 offset:4608
	s_waitcnt lgkmcnt(12)
	v_mfma_f32_32x32x16_bf16 v[2:17], v[146:149], v[122:125], v[2:17]
	v_exp_f32_e32 v66, v66
	v_exp_f32_e32 v67, v67
	v_exp_f32_e32 v68, v68
	v_exp_f32_e32 v69, v69
	ds_read_b128 v[166:169], v203 offset:6144
	ds_read_b128 v[162:165], v203 offset:6656
	s_waitcnt lgkmcnt(12)
	v_mfma_f32_32x32x16_bf16 v[18:33], v[146:149], v[98:101], v[18:33]
	v_exp_f32_e32 v70, v70
	v_exp_f32_e32 v71, v71
	v_exp_f32_e32 v72, v72
	v_exp_f32_e32 v73, v73
	s_waitcnt lgkmcnt(10)
	v_mfma_f32_32x32x16_bf16 v[2:17], v[142:145], v[102:105], v[2:17]
	v_exp_f32_e32 v74, v74
	v_exp_f32_e32 v75, v75
	v_exp_f32_e32 v76, v76
	v_exp_f32_e32 v77, v77
	s_waitcnt lgkmcnt(8)
	v_mfma_f32_32x32x16_bf16 v[18:33], v[142:145], v[106:109], v[18:33]
	v_exp_f32_e32 v78, v78
	v_exp_f32_e32 v79, v79
	v_exp_f32_e32 v80, v80
	v_exp_f32_e32 v81, v81
	s_add_i32 s6, s31, 0x2000
	s_cmpk_lg_i32 s31, 0x4000
	s_mov_b32 s24, s76
	s_cselect_b32 s76, s6, 0
	s_add_i32 s26, s26, 2
	s_cmp_ge_i32 s26, s91
	s_cbranch_scc0 .Lattn_rot
